# DF late half, last P.V: V fragments prefetched into eight idle register quads (was read-wait-MFMA one at a time)
# baseline (speedup 1.0000x reference)
.LBB0_421:
	s_andn2_b64 vcc, exec, s[10:11]
	s_cbranch_vccnz .LBB0_423
	s_lshl_b32 s2, s24, 14
	s_addk_i32 s2, 0xc000
	s_cmp_gt_i32 s24, 0
	s_cselect_b32 s2, s2, 0x10000
	s_add_i32 s2, s2, 0
	v_add_u32_e32 v0, s2, v220
	v_add_u32_e32 v0, 0x10000, v0
	ds_read_b64_tr_b16 v[80:81], v0
	ds_read_b64_tr_b16 v[82:83], v0 offset:512
	ds_read_b64_tr_b16 v[84:85], v0 offset:4096
	ds_read_b64_tr_b16 v[86:87], v0 offset:4608
	ds_read_b64_tr_b16 v[128:129], v0 offset:1024
	ds_read_b64_tr_b16 v[130:131], v0 offset:1536
	ds_read_b64_tr_b16 v[136:137], v0 offset:5120
	ds_read_b64_tr_b16 v[138:139], v0 offset:5632
	ds_read_b64_tr_b16 v[140:141], v0 offset:2048
	ds_read_b64_tr_b16 v[142:143], v0 offset:2560
	ds_read_b64_tr_b16 v[148:149], v0 offset:6144
	ds_read_b64_tr_b16 v[150:151], v0 offset:6656
	ds_read_b64_tr_b16 v[240:241], v0 offset:7168
	ds_read_b64_tr_b16 v[242:243], v0 offset:7680
	ds_read_b64_tr_b16 v[248:249], v0 offset:3072
	ds_read_b64_tr_b16 v[250:251], v0 offset:3584
	s_waitcnt lgkmcnt(14)
	v_mfma_f32_32x32x16_bf16 v[64:79], v[80:83], v[144:147], v[64:79]
	ds_read_b64_tr_b16 v[80:81], v0 offset:8192
	ds_read_b64_tr_b16 v[82:83], v0 offset:8704
	s_waitcnt lgkmcnt(14)
	v_mfma_f32_32x32x16_bf16 v[48:63], v[84:87], v[144:147], v[48:63]
	ds_read_b64_tr_b16 v[84:85], v0 offset:12288
	ds_read_b64_tr_b16 v[86:87], v0 offset:12800
	s_waitcnt lgkmcnt(14)
	v_mfma_f32_32x32x16_bf16 v[64:79], v[128:131], v[10:13], v[64:79]
	ds_read_b64_tr_b16 v[128:129], v0 offset:9216
	ds_read_b64_tr_b16 v[130:131], v0 offset:9728
	s_waitcnt lgkmcnt(14)
	v_mfma_f32_32x32x16_bf16 v[48:63], v[136:139], v[10:13], v[48:63]
	ds_read_b64_tr_b16 v[136:137], v0 offset:13312
	ds_read_b64_tr_b16 v[138:139], v0 offset:13824
	s_waitcnt lgkmcnt(14)
	v_mfma_f32_32x32x16_bf16 v[64:79], v[140:143], v[6:9], v[64:79]
	ds_read_b64_tr_b16 v[140:141], v0 offset:10240
	ds_read_b64_tr_b16 v[142:143], v0 offset:10752
	s_waitcnt lgkmcnt(14)
	v_mfma_f32_32x32x16_bf16 v[48:63], v[148:151], v[6:9], v[48:63]
	ds_read_b64_tr_b16 v[148:149], v0 offset:14336
	ds_read_b64_tr_b16 v[150:151], v0 offset:14848
	s_waitcnt lgkmcnt(14)
	v_mfma_f32_32x32x16_bf16 v[48:63], v[240:243], v[2:5], v[48:63]
	ds_read_b64_tr_b16 v[240:241], v0 offset:11264
	ds_read_b64_tr_b16 v[242:243], v0 offset:11776
	s_waitcnt lgkmcnt(14)
	v_mfma_f32_32x32x16_bf16 v[64:79], v[248:251], v[2:5], v[64:79]
	ds_read_b64_tr_b16 v[248:249], v0 offset:15360
	ds_read_b64_tr_b16 v[250:251], v0 offset:15872
	s_waitcnt lgkmcnt(14)
	v_mfma_f32_32x32x16_bf16 v[32:47], v[80:83], v[144:147], v[32:47]
	s_waitcnt lgkmcnt(12)
	v_mfma_f32_32x32x16_bf16 v[16:31], v[84:87], v[144:147], v[16:31]
	s_waitcnt lgkmcnt(10)
	v_mfma_f32_32x32x16_bf16 v[32:47], v[128:131], v[10:13], v[32:47]
	s_waitcnt lgkmcnt(8)
	v_mfma_f32_32x32x16_bf16 v[16:31], v[136:139], v[10:13], v[16:31]
	s_waitcnt lgkmcnt(6)
	v_mfma_f32_32x32x16_bf16 v[32:47], v[140:143], v[6:9], v[32:47]
	s_waitcnt lgkmcnt(4)
	v_mfma_f32_32x32x16_bf16 v[16:31], v[148:151], v[6:9], v[16:31]
	s_waitcnt lgkmcnt(2)
	v_mfma_f32_32x32x16_bf16 v[32:47], v[240:243], v[2:5], v[32:47]
	s_waitcnt lgkmcnt(0)
	v_mfma_f32_32x32x16_bf16 v[16:31], v[248:251], v[2:5], v[16:31]
